# v1 + FNet stage-1 item hand-pipelined (loads batched 10-20 in flight instead of vmcnt(0) after each)
# baseline (speedup 1.0000x reference)
.LBB0_672:
	s_andn2_saveexec_b64 s[14:15], s[14:15]
	s_cbranch_execz .LBB0_669
	v_readfirstlane_b32 s25, v66
	v_lshl_add_u32 v7, v132, 7, v70
	s_lshr_b32 s26, s25, 10
	s_and_b32 s27, s25, 0x3ff
	s_lshr_b32 s28, s27, 1
	s_and_b32 s27, s27, 1
	s_lshl_b32 s29, s26, 9
	s_add_u32 s29, s29, s28
	s_lshl_b32 s30, s29, 13
	s_lshl_b32 s31, s27, 12
	s_add_u32 s30, s30, s31
	s_add_u32 s30, s30, 0x400000
	v_add_u32_e32 v129, s30, v7
	s_lshl_b32 s29, s26, 10
	s_add_u32 s29, s29, s28
	s_lshl_b32 s29, s29, 13
	s_lshl_b32 s31, s27, 6
	s_add_u32 s29, s29, s31
	v_add_u32_e32 v142, s29, v7
	v_add_u32_e32 v143, 0x1000, v142
	v_add_u32_e32 v144, 0x400000, v142
	v_add_u32_e32 v145, 0x401000, v142
	v_lshlrev_b32_e32 v138, 7, v70
	v_lshl_add_u32 v138, v132, 3, v138
	s_lshl_b32 s31, s27, 14
	v_add_u32_e32 v138, s31, v138
	v_add_u32_e32 v139, 0x1000, v138
	v_add_u32_e32 v140, 0x2000, v138
	v_add_u32_e32 v141, 0x3000, v138
	global_load_dwordx4 v[188:191], v129, s[2:3]
	global_load_dwordx4 v[192:195], v[76:77], off
	global_load_dwordx4 v[196:199], v[78:79], off
	global_load_dwordx4 v[200:203], v[80:81], off
	global_load_dwordx4 v[204:207], v[82:83], off
	global_load_dwordx4 v[208:211], v129, s[2:3] offset:32
	global_load_dwordx4 v[212:215], v[76:77], off offset:32
	global_load_dwordx4 v[216:219], v[78:79], off offset:32
	global_load_dwordx4 v[220:223], v[80:81], off offset:32
	global_load_dwordx4 v[224:227], v[82:83], off offset:32
	global_load_dwordx4 v[228:231], v129, s[2:3] offset:64
	global_load_dwordx4 v[232:235], v[76:77], off offset:64
	global_load_dwordx4 v[236:239], v[78:79], off offset:64
	global_load_dwordx4 v[240:243], v[80:81], off offset:64
	global_load_dwordx4 v[168:171], v[82:83], off offset:64
	global_load_dwordx4 v[172:175], v129, s[2:3] offset:96
	global_load_dwordx4 v[176:179], v[76:77], off offset:96
	global_load_dwordx4 v[180:183], v[78:79], off offset:96
	global_load_dwordx4 v[58:61], v[80:81], off offset:96
	global_load_dwordx4 v[62:65], v[82:83], off offset:96
	s_waitcnt vmcnt(10)
	v_mfma_f32_32x32x16_bf16 v[10:25], v[188:191], v[192:195], 0
	v_mfma_f32_32x32x16_bf16 v[26:41], v[188:191], v[196:199], 0
	v_mfma_f32_32x32x16_bf16 v[42:57], v[188:191], v[200:203], 0
	v_mfma_f32_32x32x16_bf16 v[152:167], v[188:191], v[204:207], 0
	v_mfma_f32_32x32x16_bf16 v[10:25], v[208:211], v[212:215], v[10:25]
	v_mfma_f32_32x32x16_bf16 v[26:41], v[208:211], v[216:219], v[26:41]
	v_mfma_f32_32x32x16_bf16 v[42:57], v[208:211], v[220:223], v[42:57]
	v_mfma_f32_32x32x16_bf16 v[152:167], v[208:211], v[224:227], v[152:167]
	global_load_dwordx4 v[188:191], v129, s[4:5]
	global_load_dwordx4 v[192:195], v[76:77], off offset:128
	global_load_dwordx4 v[196:199], v[78:79], off offset:128
	global_load_dwordx4 v[200:203], v[80:81], off offset:128
	global_load_dwordx4 v[204:207], v[82:83], off offset:128
	global_load_dwordx4 v[208:211], v129, s[4:5] offset:32
	global_load_dwordx4 v[212:215], v[76:77], off offset:160
	global_load_dwordx4 v[216:219], v[78:79], off offset:160
	global_load_dwordx4 v[220:223], v[80:81], off offset:160
	global_load_dwordx4 v[224:227], v[82:83], off offset:160
	s_waitcnt vmcnt(10)
	v_mfma_f32_32x32x16_bf16 v[10:25], v[228:231], v[232:235], v[10:25]
	v_mfma_f32_32x32x16_bf16 v[26:41], v[228:231], v[236:239], v[26:41]
	v_mfma_f32_32x32x16_bf16 v[42:57], v[228:231], v[240:243], v[42:57]
	v_mfma_f32_32x32x16_bf16 v[152:167], v[228:231], v[168:171], v[152:167]
	v_mfma_f32_32x32x16_bf16 v[10:25], v[172:175], v[176:179], v[10:25]
	v_mfma_f32_32x32x16_bf16 v[26:41], v[172:175], v[180:183], v[26:41]
	v_mfma_f32_32x32x16_bf16 v[42:57], v[172:175], v[58:61], v[42:57]
	v_mfma_f32_32x32x16_bf16 v[152:167], v[172:175], v[62:65], v[152:167]
	global_load_dwordx4 v[228:231], v129, s[4:5] offset:64
	global_load_dwordx4 v[232:235], v[76:77], off offset:192
	global_load_dwordx4 v[236:239], v[78:79], off offset:192
	global_load_dwordx4 v[240:243], v[80:81], off offset:192
	global_load_dwordx4 v[168:171], v[82:83], off offset:192
	global_load_dwordx4 v[172:175], v129, s[4:5] offset:96
	global_load_dwordx4 v[176:179], v[76:77], off offset:224
	global_load_dwordx4 v[180:183], v[78:79], off offset:224
	global_load_dwordx4 v[58:61], v[80:81], off offset:224
	global_load_dwordx4 v[62:65], v[82:83], off offset:224
	s_waitcnt vmcnt(10)
	v_mfma_f32_32x32x16_bf16 v[10:25], v[188:191], v[192:195], v[10:25]
	v_mfma_f32_32x32x16_bf16 v[26:41], v[188:191], v[196:199], v[26:41]
	v_mfma_f32_32x32x16_bf16 v[42:57], v[188:191], v[200:203], v[42:57]
	v_mfma_f32_32x32x16_bf16 v[152:167], v[188:191], v[204:207], v[152:167]
	v_mfma_f32_32x32x16_bf16 v[10:25], v[208:211], v[212:215], v[10:25]
	v_mfma_f32_32x32x16_bf16 v[26:41], v[208:211], v[216:219], v[26:41]
	v_mfma_f32_32x32x16_bf16 v[42:57], v[208:211], v[220:223], v[42:57]
	v_mfma_f32_32x32x16_bf16 v[152:167], v[208:211], v[224:227], v[152:167]
	global_load_dwordx2 v[188:189], v138, s[6:7]
	global_load_dwordx2 v[190:191], v138, s[6:7] offset:512
	global_load_dwordx2 v[192:193], v138, s[6:7] offset:1024
	global_load_dwordx2 v[194:195], v138, s[6:7] offset:1536
	global_load_dwordx2 v[196:197], v139, s[6:7]
	global_load_dwordx2 v[198:199], v139, s[6:7] offset:512
	global_load_dwordx2 v[200:201], v139, s[6:7] offset:1024
	global_load_dwordx2 v[202:203], v139, s[6:7] offset:1536
	global_load_dwordx2 v[204:205], v140, s[6:7]
	global_load_dwordx2 v[206:207], v140, s[6:7] offset:512
	global_load_dwordx2 v[208:209], v140, s[6:7] offset:1024
	global_load_dwordx2 v[210:211], v140, s[6:7] offset:1536
	global_load_dwordx2 v[212:213], v141, s[6:7]
	global_load_dwordx2 v[214:215], v141, s[6:7] offset:512
	global_load_dwordx2 v[216:217], v141, s[6:7] offset:1024
	global_load_dwordx2 v[218:219], v141, s[6:7] offset:1536
	s_waitcnt vmcnt(16)
	v_mfma_f32_32x32x16_bf16 v[10:25], v[228:231], v[232:235], v[10:25]
	v_mfma_f32_32x32x16_bf16 v[26:41], v[228:231], v[236:239], v[26:41]
	v_mfma_f32_32x32x16_bf16 v[42:57], v[228:231], v[240:243], v[42:57]
	v_mfma_f32_32x32x16_bf16 v[152:167], v[228:231], v[168:171], v[152:167]
	v_mfma_f32_32x32x16_bf16 v[10:25], v[172:175], v[176:179], v[10:25]
	v_mfma_f32_32x32x16_bf16 v[26:41], v[172:175], v[180:183], v[26:41]
	v_mfma_f32_32x32x16_bf16 v[42:57], v[172:175], v[58:61], v[42:57]
	v_mfma_f32_32x32x16_bf16 v[152:167], v[172:175], v[62:65], v[152:167]
	global_load_dwordx2 v[228:229], v138, s[6:7] offset:256
	global_load_dwordx2 v[230:231], v138, s[6:7] offset:768
	global_load_dwordx2 v[232:233], v138, s[6:7] offset:1280
	global_load_dwordx2 v[234:235], v138, s[6:7] offset:1792
	global_load_dwordx2 v[236:237], v139, s[6:7] offset:256
	global_load_dwordx2 v[238:239], v139, s[6:7] offset:768
	global_load_dwordx2 v[240:241], v139, s[6:7] offset:1280
	global_load_dwordx2 v[242:243], v139, s[6:7] offset:1792
	global_load_dwordx2 v[168:169], v140, s[6:7] offset:256
	global_load_dwordx2 v[170:171], v140, s[6:7] offset:768
	global_load_dwordx2 v[172:173], v140, s[6:7] offset:1280
	global_load_dwordx2 v[174:175], v140, s[6:7] offset:1792
	global_load_dwordx2 v[176:177], v141, s[6:7] offset:256
	global_load_dwordx2 v[178:179], v141, s[6:7] offset:768
	global_load_dwordx2 v[180:181], v141, s[6:7] offset:1280
	global_load_dwordx2 v[182:183], v141, s[6:7] offset:1792
	s_waitcnt vmcnt(16)
	v_mul_f32_e32 v127, v10, v189
	v_mul_f32_e32 v129, v42, v189
	v_fma_f32 v10, v10, v188, v129
	v_fma_f32 v42, v42, v188, -v127
	v_mul_f32_e32 v127, v11, v191
	v_mul_f32_e32 v129, v43, v191
	v_fma_f32 v11, v11, v190, v129
	v_fma_f32 v43, v43, v190, -v127
	v_mul_f32_e32 v127, v12, v193
	v_mul_f32_e32 v129, v44, v193
	v_fma_f32 v12, v12, v192, v129
	v_fma_f32 v44, v44, v192, -v127
	v_mul_f32_e32 v127, v13, v195
	v_mul_f32_e32 v129, v45, v195
	v_fma_f32 v13, v13, v194, v129
	v_fma_f32 v45, v45, v194, -v127
	v_mul_f32_e32 v127, v14, v197
	v_mul_f32_e32 v129, v46, v197
	v_fma_f32 v14, v14, v196, v129
	v_fma_f32 v46, v46, v196, -v127
	v_mul_f32_e32 v127, v15, v199
	v_mul_f32_e32 v129, v47, v199
	v_fma_f32 v15, v15, v198, v129
	v_fma_f32 v47, v47, v198, -v127
	v_mul_f32_e32 v127, v16, v201
	v_mul_f32_e32 v129, v48, v201
	v_fma_f32 v16, v16, v200, v129
	v_fma_f32 v48, v48, v200, -v127
	v_mul_f32_e32 v127, v17, v203
	v_mul_f32_e32 v129, v49, v203
	v_fma_f32 v17, v17, v202, v129
	v_fma_f32 v49, v49, v202, -v127
	v_mul_f32_e32 v127, v18, v205
	v_mul_f32_e32 v129, v50, v205
	v_fma_f32 v18, v18, v204, v129
	v_fma_f32 v50, v50, v204, -v127
	v_mul_f32_e32 v127, v19, v207
	v_mul_f32_e32 v129, v51, v207
	v_fma_f32 v19, v19, v206, v129
	v_fma_f32 v51, v51, v206, -v127
	v_mul_f32_e32 v127, v20, v209
	v_mul_f32_e32 v129, v52, v209
	v_fma_f32 v20, v20, v208, v129
	v_fma_f32 v52, v52, v208, -v127
	v_mul_f32_e32 v127, v21, v211
	v_mul_f32_e32 v129, v53, v211
	v_fma_f32 v21, v21, v210, v129
	v_fma_f32 v53, v53, v210, -v127
	v_mul_f32_e32 v127, v22, v213
	v_mul_f32_e32 v129, v54, v213
	v_fma_f32 v22, v22, v212, v129
	v_fma_f32 v54, v54, v212, -v127
	v_mul_f32_e32 v127, v23, v215
	v_mul_f32_e32 v129, v55, v215
	v_fma_f32 v23, v23, v214, v129
	v_fma_f32 v55, v55, v214, -v127
	v_mul_f32_e32 v127, v24, v217
	v_mul_f32_e32 v129, v56, v217
	v_fma_f32 v24, v24, v216, v129
	v_fma_f32 v56, v56, v216, -v127
	v_mul_f32_e32 v127, v25, v219
	v_mul_f32_e32 v129, v57, v219
	v_fma_f32 v25, v25, v218, v129
	v_fma_f32 v57, v57, v218, -v127
	v_cvt_pk_bf16_f32 v10, v10, v11
	v_cvt_pk_bf16_f32 v11, v12, v13
	v_cvt_pk_bf16_f32 v12, v14, v15
	v_cvt_pk_bf16_f32 v13, v16, v17
	v_cvt_pk_bf16_f32 v42, v42, v43
	v_cvt_pk_bf16_f32 v43, v44, v45
	v_cvt_pk_bf16_f32 v44, v46, v47
	v_cvt_pk_bf16_f32 v45, v48, v49
	v_permlane32_swap_b32_e32 v10, v12
	v_permlane32_swap_b32_e32 v11, v13
	global_store_dwordx4 v142, v[10:13], s[8:9]
	v_permlane32_swap_b32_e32 v42, v44
	v_permlane32_swap_b32_e32 v43, v45
	global_store_dwordx4 v144, v[42:45], s[8:9]
	v_cvt_pk_bf16_f32 v18, v18, v19
	v_cvt_pk_bf16_f32 v19, v20, v21
	v_cvt_pk_bf16_f32 v20, v22, v23
	v_cvt_pk_bf16_f32 v21, v24, v25
	v_cvt_pk_bf16_f32 v50, v50, v51
	v_cvt_pk_bf16_f32 v51, v52, v53
	v_cvt_pk_bf16_f32 v52, v54, v55
	v_cvt_pk_bf16_f32 v53, v56, v57
	v_permlane32_swap_b32_e32 v18, v20
	v_permlane32_swap_b32_e32 v19, v21
	global_store_dwordx4 v142, v[18:21], s[8:9] offset:32
	v_permlane32_swap_b32_e32 v50, v52
	v_permlane32_swap_b32_e32 v51, v53
	global_store_dwordx4 v144, v[50:53], s[8:9] offset:32
	s_waitcnt vmcnt(4)
	v_mul_f32_e32 v127, v26, v229
	v_mul_f32_e32 v129, v152, v229
	v_fma_f32 v26, v26, v228, v129
	v_fma_f32 v152, v152, v228, -v127
	v_mul_f32_e32 v127, v27, v231
	v_mul_f32_e32 v129, v153, v231
	v_fma_f32 v27, v27, v230, v129
	v_fma_f32 v153, v153, v230, -v127
	v_mul_f32_e32 v127, v28, v233
	v_mul_f32_e32 v129, v154, v233
	v_fma_f32 v28, v28, v232, v129
	v_fma_f32 v154, v154, v232, -v127
	v_mul_f32_e32 v127, v29, v235
	v_mul_f32_e32 v129, v155, v235
	v_fma_f32 v29, v29, v234, v129
	v_fma_f32 v155, v155, v234, -v127
	v_mul_f32_e32 v127, v30, v237
	v_mul_f32_e32 v129, v156, v237
	v_fma_f32 v30, v30, v236, v129
	v_fma_f32 v156, v156, v236, -v127
	v_mul_f32_e32 v127, v31, v239
	v_mul_f32_e32 v129, v157, v239
	v_fma_f32 v31, v31, v238, v129
	v_fma_f32 v157, v157, v238, -v127
	v_mul_f32_e32 v127, v32, v241
	v_mul_f32_e32 v129, v158, v241
	v_fma_f32 v32, v32, v240, v129
	v_fma_f32 v158, v158, v240, -v127
	v_mul_f32_e32 v127, v33, v243
	v_mul_f32_e32 v129, v159, v243
	v_fma_f32 v33, v33, v242, v129
	v_fma_f32 v159, v159, v242, -v127
	v_mul_f32_e32 v127, v34, v169
	v_mul_f32_e32 v129, v160, v169
	v_fma_f32 v34, v34, v168, v129
	v_fma_f32 v160, v160, v168, -v127
	v_mul_f32_e32 v127, v35, v171
	v_mul_f32_e32 v129, v161, v171
	v_fma_f32 v35, v35, v170, v129
	v_fma_f32 v161, v161, v170, -v127
	v_mul_f32_e32 v127, v36, v173
	v_mul_f32_e32 v129, v162, v173
	v_fma_f32 v36, v36, v172, v129
	v_fma_f32 v162, v162, v172, -v127
	v_mul_f32_e32 v127, v37, v175
	v_mul_f32_e32 v129, v163, v175
	v_fma_f32 v37, v37, v174, v129
	v_fma_f32 v163, v163, v174, -v127
	v_mul_f32_e32 v127, v38, v177
	v_mul_f32_e32 v129, v164, v177
	v_fma_f32 v38, v38, v176, v129
	v_fma_f32 v164, v164, v176, -v127
	v_mul_f32_e32 v127, v39, v179
	v_mul_f32_e32 v129, v165, v179
	v_fma_f32 v39, v39, v178, v129
	v_fma_f32 v165, v165, v178, -v127
	v_mul_f32_e32 v127, v40, v181
	v_mul_f32_e32 v129, v166, v181
	v_fma_f32 v40, v40, v180, v129
	v_fma_f32 v166, v166, v180, -v127
	v_mul_f32_e32 v127, v41, v183
	v_mul_f32_e32 v129, v167, v183
	v_fma_f32 v41, v41, v182, v129
	v_fma_f32 v167, v167, v182, -v127
	v_cvt_pk_bf16_f32 v26, v26, v27
	v_cvt_pk_bf16_f32 v27, v28, v29
	v_cvt_pk_bf16_f32 v28, v30, v31
	v_cvt_pk_bf16_f32 v29, v32, v33
	v_cvt_pk_bf16_f32 v152, v152, v153
	v_cvt_pk_bf16_f32 v153, v154, v155
	v_cvt_pk_bf16_f32 v154, v156, v157
	v_cvt_pk_bf16_f32 v155, v158, v159
	v_permlane32_swap_b32_e32 v26, v28
	v_permlane32_swap_b32_e32 v27, v29
	global_store_dwordx4 v143, v[26:29], s[8:9]
	v_permlane32_swap_b32_e32 v152, v154
	v_permlane32_swap_b32_e32 v153, v155
	global_store_dwordx4 v145, v[152:155], s[8:9]
	v_cvt_pk_bf16_f32 v34, v34, v35
	v_cvt_pk_bf16_f32 v35, v36, v37
	v_cvt_pk_bf16_f32 v36, v38, v39
	v_cvt_pk_bf16_f32 v37, v40, v41
	v_cvt_pk_bf16_f32 v160, v160, v161
	v_cvt_pk_bf16_f32 v161, v162, v163
	v_cvt_pk_bf16_f32 v162, v164, v165
	v_cvt_pk_bf16_f32 v163, v166, v167
	v_permlane32_swap_b32_e32 v34, v36
	v_permlane32_swap_b32_e32 v35, v37
	global_store_dwordx4 v143, v[34:37], s[8:9] offset:32
	v_permlane32_swap_b32_e32 v160, v162
	v_permlane32_swap_b32_e32 v161, v163
	global_store_dwordx4 v145, v[160:163], s[8:9] offset:32
	s_branch .LBB0_669
